# P7 prologue: 32 row-sum partial loads issued at once (was 4 serialized groups of 8); stacks on barrier early-invalidate, epilogue and bias rewrites
# baseline (speedup 1.0000x reference)
; __global__ void __launch_bounds__(NTHR, 2) fwd_megakernel(Args a) {
;     ...
;         { const int row = ((u0.pm & ~4) | ((tid >> 8) << 2)) * 256 + (tid & 255); float sacc = 0.f;
; #pragma unroll 8
;           for (int j = 0; j < 32; ++j) sacc += part[(size_t)j * 16384 + row];
;           rstd[tid] = 1.0f / sqrtf(sacc * (1.0f / DM) + EPS); }
;         __syncthreads();
.LBB0_975:
	v_lshrrev_b32_e32 v0, 6, v186
	v_and_or_b32 v0, v0, 12, s4
	s_mov_b32 s4, 0x6050400
	v_perm_b32 v0, v0, v186, s4
	v_ashrrev_i32_e32 v1, 31, v0
	v_lshlrev_b32_e32 v17, 2, v0
	v_lshl_add_u64 v[0:1], v[0:1], 2, s[68:69]
	v_mov_b32_e32 v2, 0
	s_mov_b64 s[4:5], 0
	s_add_u32 s4, s68, 0x1f800000
	s_addc_u32 s5, s69, 0
	global_load_dword v18, v17, s[4:5]
	v_add_u32_e32 v17, 0x10000, v17
	global_load_dword v19, v17, s[4:5]
	v_add_u32_e32 v17, 0x10000, v17
	global_load_dword v20, v17, s[4:5]
	v_add_u32_e32 v17, 0x10000, v17
	global_load_dword v21, v17, s[4:5]
	v_add_u32_e32 v17, 0x10000, v17
	global_load_dword v22, v17, s[4:5]
	v_add_u32_e32 v17, 0x10000, v17
	global_load_dword v23, v17, s[4:5]
	v_add_u32_e32 v17, 0x10000, v17
	global_load_dword v24, v17, s[4:5]
	v_add_u32_e32 v17, 0x10000, v17
	global_load_dword v25, v17, s[4:5]
	v_add_u32_e32 v17, 0x10000, v17
	global_load_dword v26, v17, s[4:5]
	v_add_u32_e32 v17, 0x10000, v17
	global_load_dword v27, v17, s[4:5]
	v_add_u32_e32 v17, 0x10000, v17
	global_load_dword v28, v17, s[4:5]
	v_add_u32_e32 v17, 0x10000, v17
	global_load_dword v29, v17, s[4:5]
	v_add_u32_e32 v17, 0x10000, v17
	global_load_dword v30, v17, s[4:5]
	v_add_u32_e32 v17, 0x10000, v17
	global_load_dword v31, v17, s[4:5]
	v_add_u32_e32 v17, 0x10000, v17
	global_load_dword v32, v17, s[4:5]
	v_add_u32_e32 v17, 0x10000, v17
	global_load_dword v33, v17, s[4:5]
	v_add_u32_e32 v17, 0x10000, v17
	global_load_dword v34, v17, s[4:5]
	v_add_u32_e32 v17, 0x10000, v17
	global_load_dword v35, v17, s[4:5]
	v_add_u32_e32 v17, 0x10000, v17
	global_load_dword v36, v17, s[4:5]
	v_add_u32_e32 v17, 0x10000, v17
	global_load_dword v37, v17, s[4:5]
	v_add_u32_e32 v17, 0x10000, v17
	global_load_dword v38, v17, s[4:5]
	v_add_u32_e32 v17, 0x10000, v17
	global_load_dword v39, v17, s[4:5]
	v_add_u32_e32 v17, 0x10000, v17
	global_load_dword v40, v17, s[4:5]
	v_add_u32_e32 v17, 0x10000, v17
	global_load_dword v41, v17, s[4:5]
	v_add_u32_e32 v17, 0x10000, v17
	global_load_dword v42, v17, s[4:5]
	v_add_u32_e32 v17, 0x10000, v17
	global_load_dword v43, v17, s[4:5]
	v_add_u32_e32 v17, 0x10000, v17
	global_load_dword v44, v17, s[4:5]
	v_add_u32_e32 v17, 0x10000, v17
	global_load_dword v45, v17, s[4:5]
	v_add_u32_e32 v17, 0x10000, v17
	global_load_dword v46, v17, s[4:5]
	v_add_u32_e32 v17, 0x10000, v17
	global_load_dword v47, v17, s[4:5]
	v_add_u32_e32 v17, 0x10000, v17
	global_load_dword v48, v17, s[4:5]
	v_add_u32_e32 v17, 0x10000, v17
	global_load_dword v49, v17, s[4:5]
	s_waitcnt vmcnt(31)
	v_add_f32_e32 v2, v2, v18
	s_waitcnt vmcnt(30)
	v_add_f32_e32 v2, v2, v19
	s_waitcnt vmcnt(29)
	v_add_f32_e32 v2, v2, v20
	s_waitcnt vmcnt(28)
	v_add_f32_e32 v2, v2, v21
	s_waitcnt vmcnt(27)
	v_add_f32_e32 v2, v2, v22
	s_waitcnt vmcnt(26)
	v_add_f32_e32 v2, v2, v23
	s_waitcnt vmcnt(25)
	v_add_f32_e32 v2, v2, v24
	s_waitcnt vmcnt(24)
	v_add_f32_e32 v2, v2, v25
	s_waitcnt vmcnt(23)
	v_add_f32_e32 v2, v2, v26
	s_waitcnt vmcnt(22)
	v_add_f32_e32 v2, v2, v27
	s_waitcnt vmcnt(21)
	v_add_f32_e32 v2, v2, v28
	s_waitcnt vmcnt(20)
	v_add_f32_e32 v2, v2, v29
	s_waitcnt vmcnt(19)
	v_add_f32_e32 v2, v2, v30
	s_waitcnt vmcnt(18)
	v_add_f32_e32 v2, v2, v31
	s_waitcnt vmcnt(17)
	v_add_f32_e32 v2, v2, v32
	s_waitcnt vmcnt(16)
	v_add_f32_e32 v2, v2, v33
	s_waitcnt vmcnt(15)
	v_add_f32_e32 v2, v2, v34
	s_waitcnt vmcnt(14)
	v_add_f32_e32 v2, v2, v35
	s_waitcnt vmcnt(13)
	v_add_f32_e32 v2, v2, v36
	s_waitcnt vmcnt(12)
	v_add_f32_e32 v2, v2, v37
	s_waitcnt vmcnt(11)
	v_add_f32_e32 v2, v2, v38
	s_waitcnt vmcnt(10)
	v_add_f32_e32 v2, v2, v39
	s_waitcnt vmcnt(9)
	v_add_f32_e32 v2, v2, v40
	s_waitcnt vmcnt(8)
	v_add_f32_e32 v2, v2, v41
	s_waitcnt vmcnt(7)
	v_add_f32_e32 v2, v2, v42
	s_waitcnt vmcnt(6)
	v_add_f32_e32 v2, v2, v43
	s_waitcnt vmcnt(5)
	v_add_f32_e32 v2, v2, v44
	s_waitcnt vmcnt(4)
	v_add_f32_e32 v2, v2, v45
	s_waitcnt vmcnt(3)
	v_add_f32_e32 v2, v2, v46
	s_waitcnt vmcnt(2)
	v_add_f32_e32 v2, v2, v47
	s_waitcnt vmcnt(1)
	v_add_f32_e32 v2, v2, v48
	s_waitcnt vmcnt(0)
	v_add_f32_e32 v2, v2, v49
	v_mov_b32_e32 v0, 0x358637bd
	v_fmac_f32_e32 v0, 0x3a000000, v2
	s_mov_b32 s4, 0xf800000
	v_mul_f32_e32 v1, 0x4f800000, v0
	v_cmp_gt_f32_e32 vcc, s4, v0
	v_mov_b32_e32 v8, v186
	s_nop 0
	v_cndmask_b32_e32 v0, v0, v1, vcc
	v_sqrt_f32_e32 v1, v0
	s_nop 0
	v_add_u32_e32 v2, -1, v1
	v_fma_f32 v3, -v2, v1, v0
	v_cmp_ge_f32_e64 s[4:5], 0, v3
	v_add_u32_e32 v3, 1, v1
	s_nop 0
	v_cndmask_b32_e64 v2, v1, v2, s[4:5]
	v_fma_f32 v1, -v3, v1, v0
	v_cmp_lt_f32_e64 s[4:5], 0, v1
	s_nop 1
	v_cndmask_b32_e64 v1, v2, v3, s[4:5]
	v_mul_f32_e32 v2, 0x37800000, v1
	v_cndmask_b32_e32 v1, v1, v2, vcc
	v_mov_b32_e32 v2, 0x260
	v_cmp_class_f32_e32 vcc, v0, v2
	s_nop 1
	v_cndmask_b32_e32 v0, v1, v0, vcc
	v_div_scale_f32 v1, s[4:5], v0, v0, 1.0
	v_rcp_f32_e32 v2, v1
	s_nop 0
	v_fma_f32 v3, -v1, v2, 1.0
	v_fmac_f32_e32 v2, v3, v2
	v_div_scale_f32 v3, vcc, 1.0, v0, 1.0
	v_mul_f32_e32 v4, v3, v2
	v_fma_f32 v5, -v1, v4, v3
	v_fmac_f32_e32 v4, v5, v2
	v_fma_f32 v1, -v1, v4, v3
	v_div_fmas_f32 v1, v1, v2, v4
	v_div_fixup_f32 v0, v1, v0, 1.0
	v_add_u32_e32 v1, 0x20400, v187
	ds_write_b32 v1, v0
	s_waitcnt lgkmcnt(0)
	s_barrier
	s_andn2_b64 vcc, exec, s[2:3]
	v_readfirstlane_b32 s4, v8
	s_cbranch_vccnz .LBB0_1001
	s_ashr_i32 s30, s62, 31
	s_lshr_b32 s2, s30, 29
	s_add_i32 s5, s62, s2
	s_and_b32 s2, s5, -8
	s_sub_i32 s7, s62, s2
	s_cmp_gt_i32 s7, -1
	s_cbranch_scc0 .LBB0_980
	s_lshl_b32 s6, s7, 8
	s_cbranch_execz .LBB0_981
	s_branch .LBB0_982
